# t2 + in-proj K-loop: per-phase s_setprio flips deleted, one static s_setprio 1 for the late wave group (waves 4-7) before its loop copy (doc 7.4 form)
# baseline (speedup 1.0000x reference)
; #define PG8_STAGE(bufoff, gbase, voff) do { _Pragma("unroll") for (int _i = 0; _i < 2; ++_i) \
;         __builtin_amdgcn_global_load_lds((const unsigned*)((const char*)(gbase) + (voff)[_i]), (LAS unsigned*)(lds + (bufoff) + ldsw + _i * 8192), 16, 0, 0); } while (0)
; #define PG8_LDA(dst, b, h) do { _Pragma("unroll") for (int m = 0; m < 4; ++m) _Pragma("unroll") for (int k = 0; k < 2; ++k) dst[m][k] = *(const LAS bf16x8*)(lds + PG8_SA(b, h) + aoff + m * 2048 + k * 1024); } while (0)
; #define PG8_LDB(dst, b, h) do { _Pragma("unroll") for (int n = 0; n < 2; ++n) _Pragma("unroll") for (int k = 0; k < 2; ++k) dst[n][k] = *(const LAS bf16x8*)(lds + PG8_SB(b, h) + boff + n * 2048 + k * 1024); } while (0)
; #define PG8_MMA(ai, bj, At, Bt) do { __builtin_amdgcn_s_setprio(1); _Pragma("unroll") for (int m = 0; m < 4; ++m) _Pragma("unroll") for (int n = 0; n < 2; ++n) _Pragma("unroll") for (int k = 0; k < 2; ++k) \
;         acc[ai][bj][m][n] = __builtin_amdgcn_mfma_f32_16x16x32_bf16(Bt[n][k], At[m][k], acc[ai][bj][m][n], 0, 0, 0); __builtin_amdgcn_s_setprio(0); } while (0)
; #define PG8_WAIT_V(n) asm volatile("s_waitcnt vmcnt(" #n ")" ::: "memory")
; #define PG8_WAIT_L(n) asm volatile("s_waitcnt lgkmcnt(" #n ")" ::: "memory")
; template <class Epi, class Sched, bool ALIGN_EPI, class Hook = NoHook>
; __device__ __forceinline__ void gemm_phase(LAS unsigned char* lds, const Gemm g, const Sched& S, const Epi& E, const Hook& H = Hook()) {
;     ...
;         for (int t = tb; t < te; t += 2) {
;             const bool last = (t == nt - 2);
;             const char* a1 = cA + (size_t)(t + 1) * kstep;
;             const char* a2 = last ? nA : cA + (size_t)(t + 2) * kstep; const char* b2 = last ? nB : cB + (size_t)(t + 2) * kstep;
;             const char* a3 = a2 + kstep; const char* b3 = b2 + kstep;
;             if (last && has_next) S.a_ready(nxt);
;             PG8_LDB(B0, 0, 0); PG8_LDB(B1, 0, 1); PG8_SCHED; PG8_LDA(At, 0, 0); PG8_STAGE(PG8_SA(1, 1), a1 + hA, voffA);
;             PG8_WAIT_V(8); PG8_WAIT_L(0); PG8_BAR; PG8_MMA(0, 0, At, B0); PG8_MMA(0, 1, At, B1); PG8_BAR; PG8_SCHED;
;             PG8_LDA(At, 0, 1); PG8_STAGE(PG8_SB(0, 0), b2, voffB); PG8_STAGE(PG8_SB(0, 1), b2 + hB, voffB); PG8_STAGE(PG8_SA(0, 0), a2, voffA);
;             PG8_WAIT_V(8); PG8_WAIT_L(0); PG8_BAR; PG8_MMA(1, 0, At, B0); PG8_MMA(1, 1, At, B1); PG8_BAR; PG8_SCHED;
.LBB0_199:
	ds_read_b128 v[130:133], v217
	ds_read_b128 v[134:137], v217 offset:1024
	s_add_i32 m0, s40, 0xc000
	s_nop 0
	global_load_lds_dwordx4 v172, s[4:5]
	ds_read_b128 v[138:141], v217 offset:2048
	ds_read_b128 v[142:145], v217 offset:3072
	ds_read_b128 v[146:149], v218
	ds_read_b128 v[150:153], v218 offset:1024
	ds_read_b128 v[154:157], v218 offset:2048
	ds_read_b128 v[158:161], v218 offset:3072
	ds_read_b128 v[180:183], v219
	s_add_i32 m0, s40, 0xe000
	s_nop 0
	global_load_lds_dwordx4 v174, s[4:5]
	s_add_u32 s34, s4, 0x100
	s_addc_u32 s35, s5, 0
	s_cmp_eq_u32 s64, 60
	s_cselect_b32 s39, s7, s35
	s_cselect_b32 s38, s8, s34
	s_cselect_b32 s37, s23, s63
	s_cselect_b32 s36, s25, s31
	ds_read_b128 v[184:187], v219 offset:1024
	ds_read_b128 v[188:191], v219 offset:2048
	ds_read_b128 v[192:195], v219 offset:3072
	ds_read_b128 v[196:199], v219 offset:4096
	ds_read_b128 v[200:203], v219 offset:5120
	ds_read_b128 v[204:207], v219 offset:6144
	ds_read_b128 v[208:211], v219 offset:7168
	s_barrier
	s_waitcnt lgkmcnt(0)
	v_mfma_f32_16x16x32_bf16 v[126:129], v[130:133], v[180:183], v[126:129]
	v_mfma_f32_16x16x32_bf16 v[94:97], v[138:141], v[180:183], v[94:97]
	v_mfma_f32_16x16x32_bf16 v[122:125], v[130:133], v[188:191], v[122:125]
	v_mfma_f32_16x16x32_bf16 v[90:93], v[138:141], v[188:191], v[90:93]
	v_mfma_f32_16x16x32_bf16 v[118:121], v[130:133], v[196:199], v[118:121]
	v_mfma_f32_16x16x32_bf16 v[86:89], v[138:141], v[196:199], v[86:89]
	v_mfma_f32_16x16x32_bf16 v[114:117], v[130:133], v[204:207], v[114:117]
	v_mfma_f32_16x16x32_bf16 v[82:85], v[138:141], v[204:207], v[82:85]
	v_mfma_f32_16x16x32_bf16 v[126:129], v[134:137], v[184:187], v[126:129]
	v_mfma_f32_16x16x32_bf16 v[94:97], v[142:145], v[184:187], v[94:97]
	v_mfma_f32_16x16x32_bf16 v[122:125], v[134:137], v[192:195], v[122:125]
	v_mfma_f32_16x16x32_bf16 v[90:93], v[142:145], v[192:195], v[90:93]
	v_mfma_f32_16x16x32_bf16 v[118:121], v[134:137], v[200:203], v[118:121]
	v_mfma_f32_16x16x32_bf16 v[86:89], v[142:145], v[200:203], v[86:89]
	v_mfma_f32_16x16x32_bf16 v[114:117], v[134:137], v[208:211], v[114:117]
	v_mfma_f32_16x16x32_bf16 v[82:85], v[142:145], v[208:211], v[82:85]
	v_mfma_f32_16x16x32_bf16 v[62:65], v[146:149], v[180:183], v[62:65]
	v_mfma_f32_16x16x32_bf16 v[30:33], v[154:157], v[180:183], v[30:33]
	v_mfma_f32_16x16x32_bf16 v[58:61], v[146:149], v[188:191], v[58:61]
	v_mfma_f32_16x16x32_bf16 v[26:29], v[154:157], v[188:191], v[26:29]
	v_mfma_f32_16x16x32_bf16 v[54:57], v[146:149], v[196:199], v[54:57]
	v_mfma_f32_16x16x32_bf16 v[22:25], v[154:157], v[196:199], v[22:25]
	v_mfma_f32_16x16x32_bf16 v[50:53], v[146:149], v[204:207], v[50:53]
	v_mfma_f32_16x16x32_bf16 v[18:21], v[154:157], v[204:207], v[18:21]
	v_mfma_f32_16x16x32_bf16 v[62:65], v[150:153], v[184:187], v[62:65]
	v_mfma_f32_16x16x32_bf16 v[30:33], v[158:161], v[184:187], v[30:33]
	v_mfma_f32_16x16x32_bf16 v[58:61], v[150:153], v[192:195], v[58:61]
	v_mfma_f32_16x16x32_bf16 v[26:29], v[158:161], v[192:195], v[26:29]
	v_mfma_f32_16x16x32_bf16 v[54:57], v[150:153], v[200:203], v[54:57]
	v_mfma_f32_16x16x32_bf16 v[22:25], v[158:161], v[200:203], v[22:25]
	v_mfma_f32_16x16x32_bf16 v[50:53], v[150:153], v[208:211], v[50:53]
	v_mfma_f32_16x16x32_bf16 v[18:21], v[158:161], v[208:211], v[18:21]
	s_waitcnt vmcnt(8)
	s_barrier
	s_add_i32 s4, s59, s21
	s_mov_b32 m0, s4
	ds_read_b128 v[180:183], v219 offset:16384
	ds_read_b128 v[184:187], v219 offset:17408
	global_load_lds_dwordx4 v164, s[36:37]
	ds_read_b128 v[188:191], v219 offset:18432
	s_add_i32 m0, s4, 0x2000
	s_add_u32 s4, s36, 0x100000
	s_addc_u32 s5, s37, 0
	s_add_i32 s65, s60, s21
	global_load_lds_dwordx4 v168, s[36:37]
	ds_read_b128 v[192:195], v219 offset:19456
	s_mov_b32 m0, s65
	s_nop 0
	global_load_lds_dwordx4 v164, s[4:5]
	ds_read_b128 v[196:199], v219 offset:20480
	s_add_i32 m0, s65, 0x2000
	s_nop 0
	global_load_lds_dwordx4 v168, s[4:5]
	ds_read_b128 v[200:203], v219 offset:21504
	s_mov_b32 m0, s40
	s_nop 0
	global_load_lds_dwordx4 v162, s[38:39]
	ds_read_b128 v[204:207], v219 offset:22528
	s_mov_b32 m0, s41
	s_nop 0
	global_load_lds_dwordx4 v166, s[38:39]
	ds_read_b128 v[208:211], v219 offset:23552
	s_barrier
	s_waitcnt lgkmcnt(0)
	v_mfma_f32_16x16x32_bf16 v[110:113], v[130:133], v[180:183], v[110:113]
	v_mfma_f32_16x16x32_bf16 v[78:81], v[138:141], v[180:183], v[78:81]
	v_mfma_f32_16x16x32_bf16 v[106:109], v[130:133], v[188:191], v[106:109]
	v_mfma_f32_16x16x32_bf16 v[74:77], v[138:141], v[188:191], v[74:77]
	v_mfma_f32_16x16x32_bf16 v[102:105], v[130:133], v[196:199], v[102:105]
	v_mfma_f32_16x16x32_bf16 v[70:73], v[138:141], v[196:199], v[70:73]
	v_mfma_f32_16x16x32_bf16 v[98:101], v[130:133], v[204:207], v[98:101]
	v_mfma_f32_16x16x32_bf16 v[66:69], v[138:141], v[204:207], v[66:69]
	v_mfma_f32_16x16x32_bf16 v[110:113], v[134:137], v[184:187], v[110:113]
	v_mfma_f32_16x16x32_bf16 v[78:81], v[142:145], v[184:187], v[78:81]
	v_mfma_f32_16x16x32_bf16 v[106:109], v[134:137], v[192:195], v[106:109]
	v_mfma_f32_16x16x32_bf16 v[74:77], v[142:145], v[192:195], v[74:77]
	v_mfma_f32_16x16x32_bf16 v[102:105], v[134:137], v[200:203], v[102:105]
	v_mfma_f32_16x16x32_bf16 v[70:73], v[142:145], v[200:203], v[70:73]
	v_mfma_f32_16x16x32_bf16 v[98:101], v[134:137], v[208:211], v[98:101]
	v_mfma_f32_16x16x32_bf16 v[66:69], v[142:145], v[208:211], v[66:69]
	v_mfma_f32_16x16x32_bf16 v[46:49], v[146:149], v[180:183], v[46:49]
	v_mfma_f32_16x16x32_bf16 v[14:17], v[154:157], v[180:183], v[14:17]
	v_mfma_f32_16x16x32_bf16 v[42:45], v[146:149], v[188:191], v[42:45]
	v_mfma_f32_16x16x32_bf16 v[10:13], v[154:157], v[188:191], v[10:13]
	v_mfma_f32_16x16x32_bf16 v[38:41], v[146:149], v[196:199], v[38:41]
	v_mfma_f32_16x16x32_bf16 v[6:9], v[154:157], v[196:199], v[6:9]
	v_mfma_f32_16x16x32_bf16 v[34:37], v[146:149], v[204:207], v[34:37]
	v_mfma_f32_16x16x32_bf16 v[2:5], v[154:157], v[204:207], v[2:5]
	v_mfma_f32_16x16x32_bf16 v[46:49], v[150:153], v[184:187], v[46:49]
	v_mfma_f32_16x16x32_bf16 v[14:17], v[158:161], v[184:187], v[14:17]
	v_mfma_f32_16x16x32_bf16 v[42:45], v[150:153], v[192:195], v[42:45]
	v_mfma_f32_16x16x32_bf16 v[10:13], v[158:161], v[192:195], v[10:13]
	v_mfma_f32_16x16x32_bf16 v[38:41], v[150:153], v[200:203], v[38:41]
	v_mfma_f32_16x16x32_bf16 v[6:9], v[158:161], v[200:203], v[6:9]
	v_mfma_f32_16x16x32_bf16 v[34:37], v[150:153], v[208:211], v[34:37]
	v_mfma_f32_16x16x32_bf16 v[2:5], v[158:161], v[208:211], v[2:5]
	s_waitcnt vmcnt(8)
	s_barrier
; #define PG8_STAGE(bufoff, gbase, voff) do { _Pragma("unroll") for (int _i = 0; _i < 2; ++_i) \
;         __builtin_amdgcn_global_load_lds((const unsigned*)((const char*)(gbase) + (voff)[_i]), (LAS unsigned*)(lds + (bufoff) + ldsw + _i * 8192), 16, 0, 0); } while (0)
; #define PG8_LDA(dst, b, h) do { _Pragma("unroll") for (int m = 0; m < 4; ++m) _Pragma("unroll") for (int k = 0; k < 2; ++k) dst[m][k] = *(const LAS bf16x8*)(lds + PG8_SA(b, h) + aoff + m * 2048 + k * 1024); } while (0)
; #define PG8_LDB(dst, b, h) do { _Pragma("unroll") for (int n = 0; n < 2; ++n) _Pragma("unroll") for (int k = 0; k < 2; ++k) dst[n][k] = *(const LAS bf16x8*)(lds + PG8_SB(b, h) + boff + n * 2048 + k * 1024); } while (0)
; #define PG8_MMA(ai, bj, At, Bt) do { __builtin_amdgcn_s_setprio(1); _Pragma("unroll") for (int m = 0; m < 4; ++m) _Pragma("unroll") for (int n = 0; n < 2; ++n) _Pragma("unroll") for (int k = 0; k < 2; ++k) \
;         acc[ai][bj][m][n] = __builtin_amdgcn_mfma_f32_16x16x32_bf16(Bt[n][k], At[m][k], acc[ai][bj][m][n], 0, 0, 0); __builtin_amdgcn_s_setprio(0); } while (0)
; #define PG8_WAIT_V(n) asm volatile("s_waitcnt vmcnt(" #n ")" ::: "memory")
; #define PG8_WAIT_L(n) asm volatile("s_waitcnt lgkmcnt(" #n ")" ::: "memory")
; #define PG8_BAR __builtin_amdgcn_s_barrier()
; #define PG8_SCHED __builtin_amdgcn_sched_barrier(0)
; template <class Epi, class Sched, bool ALIGN_EPI, class Hook = NoHook>
; __device__ __forceinline__ void gemm_phase(LAS unsigned char* lds, const Gemm g, const Sched& S, const Epi& E, const Hook& H = Hook()) {
;     ...
;             PG8_LDB(B0, 1, 0); PG8_LDB(B1, 1, 1); PG8_SCHED; PG8_LDA(At, 1, 0); PG8_STAGE(PG8_SA(0, 1), a2 + hA, voffA);
;             PG8_WAIT_V(8); PG8_WAIT_L(0); PG8_BAR; PG8_MMA(0, 0, At, B0); PG8_MMA(0, 1, At, B1); PG8_BAR; PG8_SCHED;
;             PG8_LDA(At, 1, 1); PG8_STAGE(PG8_SB(1, 0), b3, voffB); PG8_STAGE(PG8_SB(1, 1), b3 + hB, voffB); PG8_STAGE(PG8_SA(1, 0), a3, voffA);
;             PG8_WAIT_V(8); PG8_WAIT_L(0); PG8_BAR; PG8_MMA(1, 0, At, B0); PG8_MMA(1, 1, At, B1); PG8_BAR; PG8_SCHED;
;         }
	s_add_i32 s65, 0, 0x18000
	s_add_i32 s66, 0, 0x1c000
	v_add_u32_e32 v142, s65, v213
	v_add_u32_e32 v158, s66, v213
	ds_read_b128 v[130:133], v142
	ds_read_b128 v[134:137], v142 offset:1024
	s_add_u32 s4, s38, 0x8000
	s_addc_u32 s5, s39, 0
	s_mov_b32 m0, s42
	s_nop 0
	global_load_lds_dwordx4 v162, s[4:5]
	ds_read_b128 v[138:141], v142 offset:2048
	ds_read_b128 v[142:145], v142 offset:3072
	ds_read_b128 v[146:149], v158
	ds_read_b128 v[150:153], v158 offset:1024
	ds_read_b128 v[154:157], v158 offset:2048
	ds_read_b128 v[158:161], v158 offset:3072
	ds_read_b128 v[180:183], v219 offset:32768
	s_mov_b32 m0, s43
	s_nop 0
	global_load_lds_dwordx4 v166, s[4:5]
	ds_read_b128 v[184:187], v219 offset:33792
	ds_read_b128 v[188:191], v219 offset:34816
	ds_read_b128 v[192:195], v219 offset:35840
	ds_read_b128 v[196:199], v219 offset:36864
	ds_read_b128 v[200:203], v219 offset:37888
	ds_read_b128 v[204:207], v219 offset:38912
	ds_read_b128 v[208:211], v219 offset:39936
	s_barrier
	s_waitcnt lgkmcnt(0)
	v_mfma_f32_16x16x32_bf16 v[126:129], v[130:133], v[180:183], v[126:129]
	v_mfma_f32_16x16x32_bf16 v[94:97], v[138:141], v[180:183], v[94:97]
	v_mfma_f32_16x16x32_bf16 v[122:125], v[130:133], v[188:191], v[122:125]
	v_mfma_f32_16x16x32_bf16 v[90:93], v[138:141], v[188:191], v[90:93]
	v_mfma_f32_16x16x32_bf16 v[118:121], v[130:133], v[196:199], v[118:121]
	v_mfma_f32_16x16x32_bf16 v[86:89], v[138:141], v[196:199], v[86:89]
	v_mfma_f32_16x16x32_bf16 v[114:117], v[130:133], v[204:207], v[114:117]
	v_mfma_f32_16x16x32_bf16 v[82:85], v[138:141], v[204:207], v[82:85]
	v_mfma_f32_16x16x32_bf16 v[126:129], v[134:137], v[184:187], v[126:129]
	v_mfma_f32_16x16x32_bf16 v[94:97], v[142:145], v[184:187], v[94:97]
	v_mfma_f32_16x16x32_bf16 v[122:125], v[134:137], v[192:195], v[122:125]
	v_mfma_f32_16x16x32_bf16 v[90:93], v[142:145], v[192:195], v[90:93]
	v_mfma_f32_16x16x32_bf16 v[118:121], v[134:137], v[200:203], v[118:121]
	v_mfma_f32_16x16x32_bf16 v[86:89], v[142:145], v[200:203], v[86:89]
	v_mfma_f32_16x16x32_bf16 v[114:117], v[134:137], v[208:211], v[114:117]
	v_mfma_f32_16x16x32_bf16 v[82:85], v[142:145], v[208:211], v[82:85]
	v_mfma_f32_16x16x32_bf16 v[62:65], v[146:149], v[180:183], v[62:65]
	v_mfma_f32_16x16x32_bf16 v[30:33], v[154:157], v[180:183], v[30:33]
	v_mfma_f32_16x16x32_bf16 v[58:61], v[146:149], v[188:191], v[58:61]
	v_mfma_f32_16x16x32_bf16 v[26:29], v[154:157], v[188:191], v[26:29]
	v_mfma_f32_16x16x32_bf16 v[54:57], v[146:149], v[196:199], v[54:57]
	v_mfma_f32_16x16x32_bf16 v[22:25], v[154:157], v[196:199], v[22:25]
	v_mfma_f32_16x16x32_bf16 v[50:53], v[146:149], v[204:207], v[50:53]
	v_mfma_f32_16x16x32_bf16 v[18:21], v[154:157], v[204:207], v[18:21]
	v_mfma_f32_16x16x32_bf16 v[62:65], v[150:153], v[184:187], v[62:65]
	v_mfma_f32_16x16x32_bf16 v[30:33], v[158:161], v[184:187], v[30:33]
	v_mfma_f32_16x16x32_bf16 v[58:61], v[150:153], v[192:195], v[58:61]
	v_mfma_f32_16x16x32_bf16 v[26:29], v[158:161], v[192:195], v[26:29]
	v_mfma_f32_16x16x32_bf16 v[54:57], v[150:153], v[200:203], v[54:57]
	v_mfma_f32_16x16x32_bf16 v[22:25], v[158:161], v[200:203], v[22:25]
	v_mfma_f32_16x16x32_bf16 v[50:53], v[150:153], v[208:211], v[50:53]
	v_mfma_f32_16x16x32_bf16 v[18:21], v[158:161], v[208:211], v[18:21]
	s_waitcnt vmcnt(8)
	s_barrier
	s_add_i32 s4, s65, s21
	s_add_u32 s68, s36, s14
	s_addc_u32 s69, s37, s15
	s_mov_b32 m0, s4
	ds_read_b128 v[180:183], v219 offset:49152
	ds_read_b128 v[184:187], v219 offset:50176
	global_load_lds_dwordx4 v164, s[68:69]
	ds_read_b128 v[188:191], v219 offset:51200
	s_add_i32 m0, s4, 0x2000
	s_add_u32 s4, s36, 0x100080
	s_addc_u32 s5, s37, 0
	s_add_i32 s36, s66, s21
	global_load_lds_dwordx4 v168, s[68:69]
	ds_read_b128 v[192:195], v219 offset:52224
	s_mov_b32 m0, s36
	s_nop 0
	global_load_lds_dwordx4 v164, s[4:5]
	ds_read_b128 v[196:199], v219 offset:53248
	s_add_i32 m0, s36, 0x2000
	s_nop 0
	global_load_lds_dwordx4 v168, s[4:5]
	ds_read_b128 v[200:203], v219 offset:54272
	s_add_u32 s70, s38, s14
	s_addc_u32 s71, s39, s15
	s_mov_b32 m0, s51
	s_nop 0
	global_load_lds_dwordx4 v162, s[70:71]
	ds_read_b128 v[204:207], v219 offset:55296
	s_mov_b32 m0, s52
	s_nop 0
	global_load_lds_dwordx4 v166, s[70:71]
	s_add_i32 s64, s64, 2
	s_add_u32 s31, s31, 0x100
	s_addc_u32 s63, s63, 0
	s_cmp_gt_u32 s64, 61
	s_mov_b64 s[4:5], s[34:35]
	ds_read_b128 v[208:211], v219 offset:56320
	s_barrier
	s_waitcnt lgkmcnt(0)
	v_mfma_f32_16x16x32_bf16 v[110:113], v[130:133], v[180:183], v[110:113]
	v_mfma_f32_16x16x32_bf16 v[78:81], v[138:141], v[180:183], v[78:81]
	v_mfma_f32_16x16x32_bf16 v[106:109], v[130:133], v[188:191], v[106:109]
	v_mfma_f32_16x16x32_bf16 v[74:77], v[138:141], v[188:191], v[74:77]
	v_mfma_f32_16x16x32_bf16 v[102:105], v[130:133], v[196:199], v[102:105]
	v_mfma_f32_16x16x32_bf16 v[70:73], v[138:141], v[196:199], v[70:73]
	v_mfma_f32_16x16x32_bf16 v[98:101], v[130:133], v[204:207], v[98:101]
	v_mfma_f32_16x16x32_bf16 v[66:69], v[138:141], v[204:207], v[66:69]
	v_mfma_f32_16x16x32_bf16 v[110:113], v[134:137], v[184:187], v[110:113]
	v_mfma_f32_16x16x32_bf16 v[78:81], v[142:145], v[184:187], v[78:81]
	v_mfma_f32_16x16x32_bf16 v[106:109], v[134:137], v[192:195], v[106:109]
	v_mfma_f32_16x16x32_bf16 v[74:77], v[142:145], v[192:195], v[74:77]
	v_mfma_f32_16x16x32_bf16 v[102:105], v[134:137], v[200:203], v[102:105]
	v_mfma_f32_16x16x32_bf16 v[70:73], v[142:145], v[200:203], v[70:73]
	v_mfma_f32_16x16x32_bf16 v[98:101], v[134:137], v[208:211], v[98:101]
	v_mfma_f32_16x16x32_bf16 v[66:69], v[142:145], v[208:211], v[66:69]
	v_mfma_f32_16x16x32_bf16 v[46:49], v[146:149], v[180:183], v[46:49]
	v_mfma_f32_16x16x32_bf16 v[14:17], v[154:157], v[180:183], v[14:17]
	v_mfma_f32_16x16x32_bf16 v[42:45], v[146:149], v[188:191], v[42:45]
	v_mfma_f32_16x16x32_bf16 v[10:13], v[154:157], v[188:191], v[10:13]
	v_mfma_f32_16x16x32_bf16 v[38:41], v[146:149], v[196:199], v[38:41]
	v_mfma_f32_16x16x32_bf16 v[6:9], v[154:157], v[196:199], v[6:9]
	v_mfma_f32_16x16x32_bf16 v[34:37], v[146:149], v[204:207], v[34:37]
	v_mfma_f32_16x16x32_bf16 v[2:5], v[154:157], v[204:207], v[2:5]
	v_mfma_f32_16x16x32_bf16 v[46:49], v[150:153], v[184:187], v[46:49]
	v_mfma_f32_16x16x32_bf16 v[14:17], v[158:161], v[184:187], v[14:17]
	v_mfma_f32_16x16x32_bf16 v[42:45], v[150:153], v[192:195], v[42:45]
	v_mfma_f32_16x16x32_bf16 v[10:13], v[158:161], v[192:195], v[10:13]
	v_mfma_f32_16x16x32_bf16 v[38:41], v[150:153], v[200:203], v[38:41]
	v_mfma_f32_16x16x32_bf16 v[6:9], v[158:161], v[200:203], v[6:9]
	v_mfma_f32_16x16x32_bf16 v[34:37], v[150:153], v[208:211], v[34:37]
	v_mfma_f32_16x16x32_bf16 v[2:5], v[158:161], v[208:211], v[2:5]
	s_waitcnt vmcnt(8)
	s_barrier
	s_cbranch_scc0 .LBB0_199
	s_branch .Lmy_d199X
; #define PG8_STAGE(bufoff, gbase, voff) do { _Pragma("unroll") for (int _i = 0; _i < 2; ++_i) \
;         __builtin_amdgcn_global_load_lds((const unsigned*)((const char*)(gbase) + (voff)[_i]), (LAS unsigned*)(lds + (bufoff) + ldsw + _i * 8192), 16, 0, 0); } while (0)
; #define PG8_LDA(dst, b, h) do { _Pragma("unroll") for (int m = 0; m < 4; ++m) _Pragma("unroll") for (int k = 0; k < 2; ++k) dst[m][k] = *(const LAS bf16x8*)(lds + PG8_SA(b, h) + aoff + m * 2048 + k * 1024); } while (0)
; #define PG8_LDB(dst, b, h) do { _Pragma("unroll") for (int n = 0; n < 2; ++n) _Pragma("unroll") for (int k = 0; k < 2; ++k) dst[n][k] = *(const LAS bf16x8*)(lds + PG8_SB(b, h) + boff + n * 2048 + k * 1024); } while (0)
; #define PG8_MMA(ai, bj, At, Bt) do { __builtin_amdgcn_s_setprio(1); _Pragma("unroll") for (int m = 0; m < 4; ++m) _Pragma("unroll") for (int n = 0; n < 2; ++n) _Pragma("unroll") for (int k = 0; k < 2; ++k) \
;         acc[ai][bj][m][n] = __builtin_amdgcn_mfma_f32_16x16x32_bf16(Bt[n][k], At[m][k], acc[ai][bj][m][n], 0, 0, 0); __builtin_amdgcn_s_setprio(0); } while (0)
; #define PG8_WAIT_V(n) asm volatile("s_waitcnt vmcnt(" #n ")" ::: "memory")
; #define PG8_WAIT_L(n) asm volatile("s_waitcnt lgkmcnt(" #n ")" ::: "memory")
; template <class Epi, class Sched, bool ALIGN_EPI, class Hook = NoHook>
; __device__ __forceinline__ void gemm_phase(LAS unsigned char* lds, const Gemm g, const Sched& S, const Epi& E, const Hook& H = Hook()) {
;     ...
;         for (int t = tb; t < te; t += 2) {
;             const bool last = (t == nt - 2);
;             const char* a1 = cA + (size_t)(t + 1) * kstep;
;             const char* a2 = last ? nA : cA + (size_t)(t + 2) * kstep; const char* b2 = last ? nB : cB + (size_t)(t + 2) * kstep;
;             const char* a3 = a2 + kstep; const char* b3 = b2 + kstep;
;             if (last && has_next) S.a_ready(nxt);
;             PG8_LDB(B0, 0, 0); PG8_LDB(B1, 0, 1); PG8_SCHED; PG8_LDA(At, 0, 0); PG8_STAGE(PG8_SA(1, 1), a1 + hA, voffA);
;             PG8_WAIT_V(8); PG8_WAIT_L(0); PG8_BAR; PG8_MMA(0, 0, At, B0); PG8_MMA(0, 1, At, B1); PG8_BAR; PG8_SCHED;
;             PG8_LDA(At, 0, 1); PG8_STAGE(PG8_SB(0, 0), b2, voffB); PG8_STAGE(PG8_SB(0, 1), b2 + hB, voffB); PG8_STAGE(PG8_SA(0, 0), a2, voffA);
;             PG8_WAIT_V(8); PG8_WAIT_L(0); PG8_BAR; PG8_MMA(1, 0, At, B0); PG8_MMA(1, 1, At, B1); PG8_BAR; PG8_SCHED;
.Lmy_d199Bin:
	s_setprio 1
.Lmy_d199B:
	ds_read_b128 v[130:133], v217
	ds_read_b128 v[134:137], v217 offset:1024
	s_add_i32 m0, s40, 0xc000
	s_nop 0
	global_load_lds_dwordx4 v172, s[4:5]
	ds_read_b128 v[138:141], v217 offset:2048
	ds_read_b128 v[142:145], v217 offset:3072
	ds_read_b128 v[146:149], v218
	ds_read_b128 v[150:153], v218 offset:1024
	ds_read_b128 v[154:157], v218 offset:2048
	ds_read_b128 v[158:161], v218 offset:3072
	ds_read_b128 v[180:183], v219
	s_add_i32 m0, s40, 0xe000
	s_nop 0
	global_load_lds_dwordx4 v174, s[4:5]
	s_add_u32 s34, s4, 0x100
	s_addc_u32 s35, s5, 0
	s_cmp_eq_u32 s64, 60
	s_cselect_b32 s39, s7, s35
	s_cselect_b32 s38, s8, s34
	s_cselect_b32 s37, s23, s63
	s_cselect_b32 s36, s25, s31
	ds_read_b128 v[184:187], v219 offset:1024
	ds_read_b128 v[188:191], v219 offset:2048
	ds_read_b128 v[192:195], v219 offset:3072
	ds_read_b128 v[196:199], v219 offset:4096
	ds_read_b128 v[200:203], v219 offset:5120
	ds_read_b128 v[204:207], v219 offset:6144
	ds_read_b128 v[208:211], v219 offset:7168
	s_waitcnt vmcnt(8) lgkmcnt(0)
	s_barrier
	v_mfma_f32_16x16x32_bf16 v[126:129], v[130:133], v[180:183], v[126:129]
	v_mfma_f32_16x16x32_bf16 v[94:97], v[138:141], v[180:183], v[94:97]
	v_mfma_f32_16x16x32_bf16 v[122:125], v[130:133], v[188:191], v[122:125]
	v_mfma_f32_16x16x32_bf16 v[90:93], v[138:141], v[188:191], v[90:93]
	v_mfma_f32_16x16x32_bf16 v[118:121], v[130:133], v[196:199], v[118:121]
	v_mfma_f32_16x16x32_bf16 v[86:89], v[138:141], v[196:199], v[86:89]
	v_mfma_f32_16x16x32_bf16 v[114:117], v[130:133], v[204:207], v[114:117]
	v_mfma_f32_16x16x32_bf16 v[82:85], v[138:141], v[204:207], v[82:85]
	v_mfma_f32_16x16x32_bf16 v[126:129], v[134:137], v[184:187], v[126:129]
	v_mfma_f32_16x16x32_bf16 v[94:97], v[142:145], v[184:187], v[94:97]
	v_mfma_f32_16x16x32_bf16 v[122:125], v[134:137], v[192:195], v[122:125]
	v_mfma_f32_16x16x32_bf16 v[90:93], v[142:145], v[192:195], v[90:93]
	v_mfma_f32_16x16x32_bf16 v[118:121], v[134:137], v[200:203], v[118:121]
	v_mfma_f32_16x16x32_bf16 v[86:89], v[142:145], v[200:203], v[86:89]
	v_mfma_f32_16x16x32_bf16 v[114:117], v[134:137], v[208:211], v[114:117]
	v_mfma_f32_16x16x32_bf16 v[82:85], v[142:145], v[208:211], v[82:85]
	v_mfma_f32_16x16x32_bf16 v[62:65], v[146:149], v[180:183], v[62:65]
	v_mfma_f32_16x16x32_bf16 v[30:33], v[154:157], v[180:183], v[30:33]
	v_mfma_f32_16x16x32_bf16 v[58:61], v[146:149], v[188:191], v[58:61]
	v_mfma_f32_16x16x32_bf16 v[26:29], v[154:157], v[188:191], v[26:29]
	v_mfma_f32_16x16x32_bf16 v[54:57], v[146:149], v[196:199], v[54:57]
	v_mfma_f32_16x16x32_bf16 v[22:25], v[154:157], v[196:199], v[22:25]
	v_mfma_f32_16x16x32_bf16 v[50:53], v[146:149], v[204:207], v[50:53]
	v_mfma_f32_16x16x32_bf16 v[18:21], v[154:157], v[204:207], v[18:21]
	v_mfma_f32_16x16x32_bf16 v[62:65], v[150:153], v[184:187], v[62:65]
	v_mfma_f32_16x16x32_bf16 v[30:33], v[158:161], v[184:187], v[30:33]
	v_mfma_f32_16x16x32_bf16 v[58:61], v[150:153], v[192:195], v[58:61]
	v_mfma_f32_16x16x32_bf16 v[26:29], v[158:161], v[192:195], v[26:29]
	v_mfma_f32_16x16x32_bf16 v[54:57], v[150:153], v[200:203], v[54:57]
	v_mfma_f32_16x16x32_bf16 v[22:25], v[158:161], v[200:203], v[22:25]
	v_mfma_f32_16x16x32_bf16 v[50:53], v[150:153], v[208:211], v[50:53]
	v_mfma_f32_16x16x32_bf16 v[18:21], v[158:161], v[208:211], v[18:21]
	s_barrier
	s_add_i32 s4, s59, s21
	s_mov_b32 m0, s4
	ds_read_b128 v[180:183], v219 offset:16384
	ds_read_b128 v[184:187], v219 offset:17408
	global_load_lds_dwordx4 v164, s[36:37]
	ds_read_b128 v[188:191], v219 offset:18432
	s_add_i32 m0, s4, 0x2000
	s_add_u32 s4, s36, 0x100000
	s_addc_u32 s5, s37, 0
	s_add_i32 s65, s60, s21
	global_load_lds_dwordx4 v168, s[36:37]
	ds_read_b128 v[192:195], v219 offset:19456
	s_mov_b32 m0, s65
	s_nop 0
	global_load_lds_dwordx4 v164, s[4:5]
	ds_read_b128 v[196:199], v219 offset:20480
	s_add_i32 m0, s65, 0x2000
	s_nop 0
	global_load_lds_dwordx4 v168, s[4:5]
	ds_read_b128 v[200:203], v219 offset:21504
	s_mov_b32 m0, s40
	s_nop 0
	global_load_lds_dwordx4 v162, s[38:39]
	ds_read_b128 v[204:207], v219 offset:22528
	s_mov_b32 m0, s41
	s_nop 0
	global_load_lds_dwordx4 v166, s[38:39]
	ds_read_b128 v[208:211], v219 offset:23552
	s_waitcnt vmcnt(8) lgkmcnt(0)
	s_barrier
	v_mfma_f32_16x16x32_bf16 v[110:113], v[130:133], v[180:183], v[110:113]
	v_mfma_f32_16x16x32_bf16 v[78:81], v[138:141], v[180:183], v[78:81]
	v_mfma_f32_16x16x32_bf16 v[106:109], v[130:133], v[188:191], v[106:109]
	v_mfma_f32_16x16x32_bf16 v[74:77], v[138:141], v[188:191], v[74:77]
	v_mfma_f32_16x16x32_bf16 v[102:105], v[130:133], v[196:199], v[102:105]
	v_mfma_f32_16x16x32_bf16 v[70:73], v[138:141], v[196:199], v[70:73]
	v_mfma_f32_16x16x32_bf16 v[98:101], v[130:133], v[204:207], v[98:101]
	v_mfma_f32_16x16x32_bf16 v[66:69], v[138:141], v[204:207], v[66:69]
	v_mfma_f32_16x16x32_bf16 v[110:113], v[134:137], v[184:187], v[110:113]
	v_mfma_f32_16x16x32_bf16 v[78:81], v[142:145], v[184:187], v[78:81]
	v_mfma_f32_16x16x32_bf16 v[106:109], v[134:137], v[192:195], v[106:109]
	v_mfma_f32_16x16x32_bf16 v[74:77], v[142:145], v[192:195], v[74:77]
	v_mfma_f32_16x16x32_bf16 v[102:105], v[134:137], v[200:203], v[102:105]
	v_mfma_f32_16x16x32_bf16 v[70:73], v[142:145], v[200:203], v[70:73]
	v_mfma_f32_16x16x32_bf16 v[98:101], v[134:137], v[208:211], v[98:101]
	v_mfma_f32_16x16x32_bf16 v[66:69], v[142:145], v[208:211], v[66:69]
	v_mfma_f32_16x16x32_bf16 v[46:49], v[146:149], v[180:183], v[46:49]
	v_mfma_f32_16x16x32_bf16 v[14:17], v[154:157], v[180:183], v[14:17]
	v_mfma_f32_16x16x32_bf16 v[42:45], v[146:149], v[188:191], v[42:45]
	v_mfma_f32_16x16x32_bf16 v[10:13], v[154:157], v[188:191], v[10:13]
	v_mfma_f32_16x16x32_bf16 v[38:41], v[146:149], v[196:199], v[38:41]
	v_mfma_f32_16x16x32_bf16 v[6:9], v[154:157], v[196:199], v[6:9]
	v_mfma_f32_16x16x32_bf16 v[34:37], v[146:149], v[204:207], v[34:37]
	v_mfma_f32_16x16x32_bf16 v[2:5], v[154:157], v[204:207], v[2:5]
	v_mfma_f32_16x16x32_bf16 v[46:49], v[150:153], v[184:187], v[46:49]
	v_mfma_f32_16x16x32_bf16 v[14:17], v[158:161], v[184:187], v[14:17]
	v_mfma_f32_16x16x32_bf16 v[42:45], v[150:153], v[192:195], v[42:45]
	v_mfma_f32_16x16x32_bf16 v[10:13], v[158:161], v[192:195], v[10:13]
	v_mfma_f32_16x16x32_bf16 v[38:41], v[150:153], v[200:203], v[38:41]
	v_mfma_f32_16x16x32_bf16 v[6:9], v[158:161], v[200:203], v[6:9]
	v_mfma_f32_16x16x32_bf16 v[34:37], v[150:153], v[208:211], v[34:37]
	v_mfma_f32_16x16x32_bf16 v[2:5], v[158:161], v[208:211], v[2:5]
	s_barrier
; #define PG8_STAGE(bufoff, gbase, voff) do { _Pragma("unroll") for (int _i = 0; _i < 2; ++_i) \
;         __builtin_amdgcn_global_load_lds((const unsigned*)((const char*)(gbase) + (voff)[_i]), (LAS unsigned*)(lds + (bufoff) + ldsw + _i * 8192), 16, 0, 0); } while (0)
; #define PG8_LDA(dst, b, h) do { _Pragma("unroll") for (int m = 0; m < 4; ++m) _Pragma("unroll") for (int k = 0; k < 2; ++k) dst[m][k] = *(const LAS bf16x8*)(lds + PG8_SA(b, h) + aoff + m * 2048 + k * 1024); } while (0)
; #define PG8_LDB(dst, b, h) do { _Pragma("unroll") for (int n = 0; n < 2; ++n) _Pragma("unroll") for (int k = 0; k < 2; ++k) dst[n][k] = *(const LAS bf16x8*)(lds + PG8_SB(b, h) + boff + n * 2048 + k * 1024); } while (0)
; #define PG8_MMA(ai, bj, At, Bt) do { __builtin_amdgcn_s_setprio(1); _Pragma("unroll") for (int m = 0; m < 4; ++m) _Pragma("unroll") for (int n = 0; n < 2; ++n) _Pragma("unroll") for (int k = 0; k < 2; ++k) \
;         acc[ai][bj][m][n] = __builtin_amdgcn_mfma_f32_16x16x32_bf16(Bt[n][k], At[m][k], acc[ai][bj][m][n], 0, 0, 0); __builtin_amdgcn_s_setprio(0); } while (0)
; #define PG8_WAIT_V(n) asm volatile("s_waitcnt vmcnt(" #n ")" ::: "memory")
; #define PG8_WAIT_L(n) asm volatile("s_waitcnt lgkmcnt(" #n ")" ::: "memory")
; #define PG8_BAR __builtin_amdgcn_s_barrier()
;     __device__ __forceinline__ void operator()(const f32x4 (&acc)[2][2][4][2], const Unit& u, int wr, int wc, int fr, int fq) const {
;         if (u.pn >= TX0 && u.pn < TQ0) { conv_tile(acc, u, wr, wc, fr, fq); return; }
; template <class Epi, class Sched, bool ALIGN_EPI, class Hook = NoHook>
; __device__ __forceinline__ void gemm_phase(LAS unsigned char* lds, const Gemm g, const Sched& S, const Epi& E, const Hook& H = Hook()) {
;     ...
;             PG8_LDB(B0, 1, 0); PG8_LDB(B1, 1, 1); PG8_SCHED; PG8_LDA(At, 1, 0); PG8_STAGE(PG8_SA(0, 1), a2 + hA, voffA);
;             PG8_WAIT_V(8); PG8_WAIT_L(0); PG8_BAR; PG8_MMA(0, 0, At, B0); PG8_MMA(0, 1, At, B1); PG8_BAR; PG8_SCHED;
;             PG8_LDA(At, 1, 1); PG8_STAGE(PG8_SB(1, 0), b3, voffB); PG8_STAGE(PG8_SB(1, 1), b3 + hB, voffB); PG8_STAGE(PG8_SA(1, 0), a3, voffA);
;             PG8_WAIT_V(8); PG8_WAIT_L(0); PG8_BAR; PG8_MMA(1, 0, At, B0); PG8_MMA(1, 1, At, B1); PG8_BAR; PG8_SCHED;
;         }
;         if constexpr (Hook::ON) H.after(te, acc, cur, wr, wc, fr, fq);
;         }
;         if constexpr (ALIGN_EPI) { if (wr == 0) PG8_BAR; }
	s_add_i32 s65, 0, 0x18000
	s_add_i32 s66, 0, 0x1c000
	v_add_u32_e32 v142, s65, v213
	v_add_u32_e32 v158, s66, v213
	ds_read_b128 v[130:133], v142
	ds_read_b128 v[134:137], v142 offset:1024
	s_add_u32 s4, s38, 0x8000
	s_addc_u32 s5, s39, 0
	s_mov_b32 m0, s42
	s_nop 0
	global_load_lds_dwordx4 v162, s[4:5]
	ds_read_b128 v[138:141], v142 offset:2048
	ds_read_b128 v[142:145], v142 offset:3072
	ds_read_b128 v[146:149], v158
	ds_read_b128 v[150:153], v158 offset:1024
	ds_read_b128 v[154:157], v158 offset:2048
	ds_read_b128 v[158:161], v158 offset:3072
	ds_read_b128 v[180:183], v219 offset:32768
	s_mov_b32 m0, s43
	s_nop 0
	global_load_lds_dwordx4 v166, s[4:5]
	ds_read_b128 v[184:187], v219 offset:33792
	ds_read_b128 v[188:191], v219 offset:34816
	ds_read_b128 v[192:195], v219 offset:35840
	ds_read_b128 v[196:199], v219 offset:36864
	ds_read_b128 v[200:203], v219 offset:37888
	ds_read_b128 v[204:207], v219 offset:38912
	ds_read_b128 v[208:211], v219 offset:39936
	s_waitcnt vmcnt(8) lgkmcnt(0)
	s_barrier
	v_mfma_f32_16x16x32_bf16 v[126:129], v[130:133], v[180:183], v[126:129]
	v_mfma_f32_16x16x32_bf16 v[94:97], v[138:141], v[180:183], v[94:97]
	v_mfma_f32_16x16x32_bf16 v[122:125], v[130:133], v[188:191], v[122:125]
	v_mfma_f32_16x16x32_bf16 v[90:93], v[138:141], v[188:191], v[90:93]
	v_mfma_f32_16x16x32_bf16 v[118:121], v[130:133], v[196:199], v[118:121]
	v_mfma_f32_16x16x32_bf16 v[86:89], v[138:141], v[196:199], v[86:89]
	v_mfma_f32_16x16x32_bf16 v[114:117], v[130:133], v[204:207], v[114:117]
	v_mfma_f32_16x16x32_bf16 v[82:85], v[138:141], v[204:207], v[82:85]
	v_mfma_f32_16x16x32_bf16 v[126:129], v[134:137], v[184:187], v[126:129]
	v_mfma_f32_16x16x32_bf16 v[94:97], v[142:145], v[184:187], v[94:97]
	v_mfma_f32_16x16x32_bf16 v[122:125], v[134:137], v[192:195], v[122:125]
	v_mfma_f32_16x16x32_bf16 v[90:93], v[142:145], v[192:195], v[90:93]
	v_mfma_f32_16x16x32_bf16 v[118:121], v[134:137], v[200:203], v[118:121]
	v_mfma_f32_16x16x32_bf16 v[86:89], v[142:145], v[200:203], v[86:89]
	v_mfma_f32_16x16x32_bf16 v[114:117], v[134:137], v[208:211], v[114:117]
	v_mfma_f32_16x16x32_bf16 v[82:85], v[142:145], v[208:211], v[82:85]
	v_mfma_f32_16x16x32_bf16 v[62:65], v[146:149], v[180:183], v[62:65]
	v_mfma_f32_16x16x32_bf16 v[30:33], v[154:157], v[180:183], v[30:33]
	v_mfma_f32_16x16x32_bf16 v[58:61], v[146:149], v[188:191], v[58:61]
	v_mfma_f32_16x16x32_bf16 v[26:29], v[154:157], v[188:191], v[26:29]
	v_mfma_f32_16x16x32_bf16 v[54:57], v[146:149], v[196:199], v[54:57]
	v_mfma_f32_16x16x32_bf16 v[22:25], v[154:157], v[196:199], v[22:25]
	v_mfma_f32_16x16x32_bf16 v[50:53], v[146:149], v[204:207], v[50:53]
	v_mfma_f32_16x16x32_bf16 v[18:21], v[154:157], v[204:207], v[18:21]
	v_mfma_f32_16x16x32_bf16 v[62:65], v[150:153], v[184:187], v[62:65]
	v_mfma_f32_16x16x32_bf16 v[30:33], v[158:161], v[184:187], v[30:33]
	v_mfma_f32_16x16x32_bf16 v[58:61], v[150:153], v[192:195], v[58:61]
	v_mfma_f32_16x16x32_bf16 v[26:29], v[158:161], v[192:195], v[26:29]
	v_mfma_f32_16x16x32_bf16 v[54:57], v[150:153], v[200:203], v[54:57]
	v_mfma_f32_16x16x32_bf16 v[22:25], v[158:161], v[200:203], v[22:25]
	v_mfma_f32_16x16x32_bf16 v[50:53], v[150:153], v[208:211], v[50:53]
	v_mfma_f32_16x16x32_bf16 v[18:21], v[158:161], v[208:211], v[18:21]
	s_barrier
	s_add_i32 s4, s65, s21
	s_add_u32 s68, s36, s14
	s_addc_u32 s69, s37, s15
	s_mov_b32 m0, s4
	ds_read_b128 v[180:183], v219 offset:49152
	ds_read_b128 v[184:187], v219 offset:50176
	global_load_lds_dwordx4 v164, s[68:69]
	ds_read_b128 v[188:191], v219 offset:51200
	s_add_i32 m0, s4, 0x2000
	s_add_u32 s4, s36, 0x100080
	s_addc_u32 s5, s37, 0
	s_add_i32 s36, s66, s21
	global_load_lds_dwordx4 v168, s[68:69]
	ds_read_b128 v[192:195], v219 offset:52224
	s_mov_b32 m0, s36
	s_nop 0
	global_load_lds_dwordx4 v164, s[4:5]
	ds_read_b128 v[196:199], v219 offset:53248
	s_add_i32 m0, s36, 0x2000
	s_nop 0
	global_load_lds_dwordx4 v168, s[4:5]
	ds_read_b128 v[200:203], v219 offset:54272
	s_add_u32 s70, s38, s14
	s_addc_u32 s71, s39, s15
	s_mov_b32 m0, s51
	s_nop 0
	global_load_lds_dwordx4 v162, s[70:71]
	ds_read_b128 v[204:207], v219 offset:55296
	s_mov_b32 m0, s52
	s_nop 0
	global_load_lds_dwordx4 v166, s[70:71]
	s_add_i32 s64, s64, 2
	s_add_u32 s31, s31, 0x100
	s_addc_u32 s63, s63, 0
	s_cmp_gt_u32 s64, 61
	s_mov_b64 s[4:5], s[34:35]
	ds_read_b128 v[208:211], v219 offset:56320
	s_waitcnt vmcnt(8) lgkmcnt(0)
	s_barrier
	v_mfma_f32_16x16x32_bf16 v[110:113], v[130:133], v[180:183], v[110:113]
	v_mfma_f32_16x16x32_bf16 v[78:81], v[138:141], v[180:183], v[78:81]
	v_mfma_f32_16x16x32_bf16 v[106:109], v[130:133], v[188:191], v[106:109]
	v_mfma_f32_16x16x32_bf16 v[74:77], v[138:141], v[188:191], v[74:77]
	v_mfma_f32_16x16x32_bf16 v[102:105], v[130:133], v[196:199], v[102:105]
	v_mfma_f32_16x16x32_bf16 v[70:73], v[138:141], v[196:199], v[70:73]
	v_mfma_f32_16x16x32_bf16 v[98:101], v[130:133], v[204:207], v[98:101]
	v_mfma_f32_16x16x32_bf16 v[66:69], v[138:141], v[204:207], v[66:69]
	v_mfma_f32_16x16x32_bf16 v[110:113], v[134:137], v[184:187], v[110:113]
	v_mfma_f32_16x16x32_bf16 v[78:81], v[142:145], v[184:187], v[78:81]
	v_mfma_f32_16x16x32_bf16 v[106:109], v[134:137], v[192:195], v[106:109]
	v_mfma_f32_16x16x32_bf16 v[74:77], v[142:145], v[192:195], v[74:77]
	v_mfma_f32_16x16x32_bf16 v[102:105], v[134:137], v[200:203], v[102:105]
	v_mfma_f32_16x16x32_bf16 v[70:73], v[142:145], v[200:203], v[70:73]
	v_mfma_f32_16x16x32_bf16 v[98:101], v[134:137], v[208:211], v[98:101]
	v_mfma_f32_16x16x32_bf16 v[66:69], v[142:145], v[208:211], v[66:69]
	v_mfma_f32_16x16x32_bf16 v[46:49], v[146:149], v[180:183], v[46:49]
	v_mfma_f32_16x16x32_bf16 v[14:17], v[154:157], v[180:183], v[14:17]
	v_mfma_f32_16x16x32_bf16 v[42:45], v[146:149], v[188:191], v[42:45]
	v_mfma_f32_16x16x32_bf16 v[10:13], v[154:157], v[188:191], v[10:13]
	v_mfma_f32_16x16x32_bf16 v[38:41], v[146:149], v[196:199], v[38:41]
	v_mfma_f32_16x16x32_bf16 v[6:9], v[154:157], v[196:199], v[6:9]
	v_mfma_f32_16x16x32_bf16 v[34:37], v[146:149], v[204:207], v[34:37]
	v_mfma_f32_16x16x32_bf16 v[2:5], v[154:157], v[204:207], v[2:5]
	v_mfma_f32_16x16x32_bf16 v[46:49], v[150:153], v[184:187], v[46:49]
	v_mfma_f32_16x16x32_bf16 v[14:17], v[158:161], v[184:187], v[14:17]
	v_mfma_f32_16x16x32_bf16 v[42:45], v[150:153], v[192:195], v[42:45]
	v_mfma_f32_16x16x32_bf16 v[10:13], v[158:161], v[192:195], v[10:13]
	v_mfma_f32_16x16x32_bf16 v[38:41], v[150:153], v[200:203], v[38:41]
	v_mfma_f32_16x16x32_bf16 v[6:9], v[158:161], v[200:203], v[6:9]
	v_mfma_f32_16x16x32_bf16 v[34:37], v[150:153], v[208:211], v[34:37]
	v_mfma_f32_16x16x32_bf16 v[2:5], v[158:161], v[208:211], v[2:5]
	s_barrier
	s_cbranch_scc0 .Lmy_d199B
.Lmy_d199X:
	s_setprio 0
	s_and_b64 vcc, exec, s[18:19]
	s_cbranch_vccz .LBB0_203
	s_barrier
	s_sub_i32 s4, s6, 32
	s_cmp_gt_u32 s4, 39
	s_mov_b64 s[4:5], -1
	s_cbranch_scc1 .LBB0_204
